# MLA loop: counted vmcnt(2) waits per register set (K/V fetched two tiles ahead stay in flight); dropped dead adds in GU hit path
# baseline (speedup 1.0000x reference)
; template <int NP> __device__ __forceinline__ void load_rstd8(const float* ss, const Unit& u, int wr, int fr, int fq, float inv_n, float (&rs)[2][4]) {
;     f32x4 v[2][4];
; #pragma unroll
;     for (int ai = 0; ai < 2; ++ai)
; #pragma unroll
;         for (int m = 0; m < 4; ++m) { const int row = u.pm * BM + ai * HALF + wr * 64 + m * 16 + fr; v[ai][m] = *(const f32x4*)(ss + (size_t)row * NP + (NP == 16 ? 4 * fq : 0)); }
; #pragma unroll
;     for (int ai = 0; ai < 2; ++ai)
; #pragma unroll
;         for (int m = 0; m < 4; ++m) { float t = (v[ai][m][0] + v[ai][m][1]) + (v[ai][m][2] + v[ai][m][3]); if (NP == 16) t = quad_sum(t); rs[ai][m] = __builtin_amdgcn_rsqf(t * inv_n + kEps); }
; }
;     __device__ __forceinline__ void operator()(const f32x4 (&acc)[2][2][4][2], const Unit& u, int wr, int wc, int fr, int fq) const {
;         float rsv[2][4]; load_rstd8<16>(ss, u, wr, fr, fq, 1.0f / 1024.0f, rsv);
.LBB0_194:
	s_lshl_b32 s34, s73, 8
	v_add_u32_e32 v162, s34, v147
	v_lshlrev_b32_e32 v170, 2, v238
	v_add_u32_e32 v170, 0x20000, v170
	ds_read_b32 v171, v170
	ds_read_b32 v164, v170 offset:2048
	ds_read_b32 v166, v170 offset:4096
	ds_read_b32 v160, v170 offset:6144
	ds_read_b32 v156, v170 offset:8192
	ds_read_b32 v154, v170 offset:10240
	ds_read_b32 v150, v170 offset:12288
	ds_read_b32 v158, v170 offset:14336
	ds_read_b32 v146, v170 offset:16384
	s_waitcnt lgkmcnt(0)
	v_cmp_eq_u32_e32 vcc, s73, v171
	s_nop 4
	s_cbranch_vccnz .Lgu_rs_hit
	v_ashrrev_i32_e32 v163, 31, v162
	v_or_b32_e32 v144, 16, v162
	v_lshlrev_b64 v[142:143], 6, v[162:163]
	v_ashrrev_i32_e32 v145, 31, v144
	v_lshl_add_u64 v[142:143], v[136:137], 0, v[142:143]
	v_lshlrev_b64 v[144:145], 6, v[144:145]
	v_lshl_add_u64 v[144:145], v[136:137], 0, v[144:145]
	global_load_dwordx4 v[164:167], v[142:143], off
	global_load_dwordx4 v[168:171], v[144:145], off
	v_or_b32_e32 v142, 32, v162
	v_ashrrev_i32_e32 v143, 31, v142
	v_or_b32_e32 v144, 48, v162
	v_lshlrev_b64 v[142:143], 6, v[142:143]
	v_ashrrev_i32_e32 v145, 31, v144
	v_add_u32_e32 v152, 0x80, v162
	v_lshl_add_u64 v[142:143], v[136:137], 0, v[142:143]
	v_lshlrev_b64 v[144:145], 6, v[144:145]
	v_ashrrev_i32_e32 v153, 31, v152
	v_lshl_add_u64 v[144:145], v[136:137], 0, v[144:145]
	global_load_dwordx4 v[172:175], v[142:143], off
	global_load_dwordx4 v[176:179], v[144:145], off
	v_lshlrev_b64 v[142:143], 6, v[152:153]
	v_lshl_add_u64 v[142:143], v[136:137], 0, v[142:143]
	global_load_dwordx4 v[180:183], v[142:143], off
	v_add_u32_e32 v148, 0x90, v162
	v_ashrrev_i32_e32 v149, 31, v148
	v_lshlrev_b64 v[142:143], 6, v[148:149]
	v_lshl_add_u64 v[142:143], v[136:137], 0, v[142:143]
	global_load_dwordx4 v[184:187], v[142:143], off
	v_add_u32_e32 v144, 0xa0, v162
	v_add_u32_e32 v142, 0xb0, v162
	v_ashrrev_i32_e32 v145, 31, v144
	v_ashrrev_i32_e32 v143, 31, v142
	v_lshlrev_b64 v[188:189], 6, v[144:145]
	v_lshlrev_b64 v[190:191], 6, v[142:143]
	v_lshl_add_u64 v[188:189], v[136:137], 0, v[188:189]
	v_lshl_add_u64 v[192:193], v[136:137], 0, v[190:191]
	global_load_dwordx4 v[188:191], v[188:189], off
	s_nop 0
	global_load_dwordx4 v[192:195], v[192:193], off
	s_waitcnt vmcnt(0)
	v_add_f32_e32 v143, v164, v165
	v_add_f32_e32 v145, v166, v167
	v_add_f32_e32 v143, v143, v145
	v_add_f32_e32 v145, v168, v169
	v_add_f32_e32 v146, v170, v171
	v_mov_b32_e32 v160, v143
	v_add_f32_e32 v145, v145, v146
	s_nop 0
	v_permlane16_swap_b32_e32 v143, v160
	v_add_f32_e32 v143, v143, v160
	v_add_f32_e32 v149, v172, v173
	v_add_f32_e32 v150, v174, v175
	v_add_f32_e32 v153, v176, v177
	v_add_f32_e32 v154, v178, v179
	v_add_f32_e32 v146, v149, v150
	v_add_f32_e32 v149, v153, v154
	v_mov_b32_e32 v153, v145
	v_add_f32_e32 v156, v180, v181
	v_add_f32_e32 v158, v182, v183
	v_permlane16_swap_b32_e32 v145, v153
	v_add_f32_e32 v150, v156, v158
	v_mov_b32_e32 v158, v143
	v_add_f32_e32 v145, v145, v153
	v_mov_b32_e32 v154, v146
	v_permlane32_swap_b32_e32 v143, v158
	v_mov_b32_e32 v153, v145
	v_permlane16_swap_b32_e32 v146, v154
	v_add_f32_e32 v143, v143, v158
	v_permlane32_swap_b32_e32 v145, v153
	v_add_f32_e32 v146, v146, v154
	v_fmamk_f32 v143, v143, 0x3a800000, v240
	v_add_f32_e32 v145, v145, v153
	v_mov_b32_e32 v154, v146
	v_rsq_f32_e32 v164, v143
	v_fmamk_f32 v143, v145, 0x3a800000, v240
	v_permlane32_swap_b32_e32 v146, v154
	v_rsq_f32_e32 v166, v143
	v_mov_b32_e32 v143, v150
	v_add_f32_e32 v146, v146, v154
	s_nop 0
	v_permlane16_swap_b32_e32 v150, v143
	v_mov_b32_e32 v156, v149
	v_fmamk_f32 v145, v146, 0x3a800000, v240
	v_add_f32_e32 v143, v150, v143
	v_permlane16_swap_b32_e32 v149, v156
	v_rsq_f32_e32 v160, v145
	v_mov_b32_e32 v145, v143
	v_add_f32_e32 v149, v149, v156
	s_nop 0
	v_permlane32_swap_b32_e32 v143, v145
	v_mov_b32_e32 v156, v149
	v_add_f32_e32 v143, v143, v145
	s_nop 0
	v_permlane32_swap_b32_e32 v149, v156
	v_fmamk_f32 v143, v143, 0x3a800000, v240
	v_add_f32_e32 v149, v149, v156
	v_rsq_f32_e32 v156, v143
	v_add_f32_e32 v143, v184, v185
	v_add_f32_e32 v145, v186, v187
	v_add_f32_e32 v143, v143, v145
	v_mov_b32_e32 v145, v143
	s_nop 1
	v_permlane16_swap_b32_e32 v143, v145
	v_add_f32_e32 v143, v143, v145
	v_mov_b32_e32 v145, v143
	s_nop 1
	v_permlane32_swap_b32_e32 v143, v145
	v_add_f32_e32 v143, v143, v145
	v_fmamk_f32 v143, v143, 0x3a800000, v240
	v_rsq_f32_e32 v154, v143
	v_add_f32_e32 v143, v188, v189
	v_add_f32_e32 v145, v190, v191
	v_add_f32_e32 v143, v143, v145
	v_mov_b32_e32 v145, v143
	s_nop 1
	v_permlane16_swap_b32_e32 v143, v145
	v_add_f32_e32 v143, v143, v145
	v_mov_b32_e32 v145, v143
	s_nop 1
	v_permlane32_swap_b32_e32 v143, v145
	v_add_f32_e32 v143, v143, v145
	v_fmamk_f32 v143, v143, 0x3a800000, v240
	v_rsq_f32_e32 v150, v143
	v_add_f32_e32 v143, v192, v193
	v_add_f32_e32 v145, v194, v195
	v_add_f32_e32 v143, v143, v145
	v_mov_b32_e32 v145, v143
	s_nop 1
	v_permlane16_swap_b32_e32 v143, v145
	v_add_f32_e32 v143, v143, v145
	v_mov_b32_e32 v145, v143
	s_nop 1
	v_permlane32_swap_b32_e32 v143, v145
	v_add_f32_e32 v143, v143, v145
	v_fmamk_f32 v146, v149, 0x3a800000, v240
	v_fmamk_f32 v143, v143, 0x3a800000, v240
	v_rsq_f32_e32 v158, v146
	v_rsq_f32_e32 v146, v143
	v_lshlrev_b32_e32 v170, 2, v238
	v_add_u32_e32 v170, 0x20000, v170
	v_mov_b32_e32 v171, s73
	ds_write_b32 v170, v171
	ds_write_b32 v170, v164 offset:2048
	ds_write_b32 v170, v166 offset:4096
	ds_write_b32 v170, v160 offset:6144
	ds_write_b32 v170, v156 offset:8192
	ds_write_b32 v170, v154 offset:10240
	ds_write_b32 v170, v150 offset:12288
	ds_write_b32 v170, v158 offset:14336
	ds_write_b32 v170, v146 offset:16384

; #define ATT_FETCH(KR0, KR1, VR, tt) do { const size_t kb_ = (size_t)(tt) * 64; \
;         KR0 = *(const u32x4*)(K + (kb_ + kkey0) * ldk + kch0 * 8); \
;         if (k2) KR1 = *(const u32x4*)(K + (kb_ + kkey1) * ldk + kch1 * 8); \
;         VR = *(const u32x4*)(V + (kb_ + vkey) * ldv + vch * 8); } while (0)
; template <int DK, int MODE>
; __device__ __forceinline__ void attn_unit(const bf16_t* Q, int ldq, const bf16_t* K, int ldk, const bf16_t* V, int ldv, bf16_t* O, int ldo, int qb, char* shm, float sc) {
;     ...
;     ATT_FETCH(kr0A, kr1A, vrA, ATT_TILE(0)); ATT_FETCH(kr0B, kr1B, vrB, ATT_TILE(1));
;     bool done = false;
.LBB0_1361:
	s_waitcnt vmcnt(2)
	ds_write_b128 v137, v[88:91]
	s_and_saveexec_b64 s[0:1], s[38:39]
	ds_write_b128 v138, v[92:95]
	s_or_b64 exec, exec, s[0:1]
	s_add_i32 s36, s34, -1
	s_cmp_lt_u32 s36, s11
	s_cselect_b32 s18, s36, s35
	s_lshl_b64 s[0:1], s[18:19], 6
	v_lshl_add_u64 v[32:33], s[0:1], 0, v[114:115]
	v_mad_u64_u32 v[34:35], s[28:29], v32, s83, v[120:121]
	v_mad_i32_i24 v35, v33, s83, v35
	ds_write_b128 v139, v[100:103] offset:13312
	s_waitcnt lgkmcnt(0)
	s_barrier
	global_load_dwordx4 v[88:91], v[34:35], off
	s_and_saveexec_b64 s[28:29], s[38:39]
	s_cbranch_execz .LBB0_1365
	v_lshl_add_u64 v[32:33], s[0:1], 0, v[116:117]
	v_mad_u64_u32 v[34:35], s[40:41], v32, s83, v[124:125]
	v_mad_i32_i24 v35, v33, s83, v35
	global_load_dwordx4 v[92:95], v[34:35], off

; #define ATT_FETCH(KR0, KR1, VR, tt) do { const size_t kb_ = (size_t)(tt) * 64; \
;         KR0 = *(const u32x4*)(K + (kb_ + kkey0) * ldk + kch0 * 8); \
;         if (k2) KR1 = *(const u32x4*)(K + (kb_ + kkey1) * ldk + kch1 * 8); \
;         VR = *(const u32x4*)(V + (kb_ + vkey) * ldv + vch * 8); } while (0)
; template <int DK, int MODE>
; __device__ __forceinline__ void attn_unit(const bf16_t* Q, int ldq, const bf16_t* K, int ldk, const bf16_t* V, int ldv, bf16_t* O, int ldo, int qb, char* shm, float sc) {
;     ...
;     ATT_FETCH(kr0A, kr1A, vrA, ATT_TILE(0)); ATT_FETCH(kr0B, kr1B, vrB, ATT_TILE(1));
;     bool done = false;
.LBB0_1369:
	s_waitcnt vmcnt(2)
	ds_write_b128 v137, v[96:99] offset:21504
	s_and_saveexec_b64 s[0:1], s[38:39]
	ds_write_b128 v138, v[104:107] offset:21504
	s_or_b64 exec, exec, s[0:1]
	s_cmp_lt_u32 s34, s11
	s_cselect_b32 s18, s34, s35
	s_lshl_b64 s[0:1], s[18:19], 6
	v_lshl_add_u64 v[32:33], s[0:1], 0, v[114:115]
	v_mad_u64_u32 v[34:35], s[28:29], v32, s83, v[120:121]
	v_mad_i32_i24 v35, v33, s83, v35
	ds_write_b128 v139, v[108:111] offset:34816
	s_waitcnt lgkmcnt(0)
	s_barrier
	global_load_dwordx4 v[96:99], v[34:35], off
	s_and_saveexec_b64 s[28:29], s[38:39]
	s_cbranch_execz .LBB0_1373
	v_lshl_add_u64 v[32:33], s[0:1], 0, v[116:117]
	v_mad_u64_u32 v[34:35], s[40:41], v32, s83, v[124:125]
	v_mad_i32_i24 v35, v33, s83, v35
	global_load_dwordx4 v[104:107], v[34:35], off
